# v20 plus q/k epilogue row-sum via v_permlane16/32_swap instead of two ds_bpermute round trips (hipcc setprio flips kept)
# baseline (speedup 1.0000x reference)
;     __device__ __forceinline__ void operator()(const f32x4 (&acc)[2][2][4][2], const Unit& u, int wr, int wc, int fr, int fq) const {
;     ...
;         if (colt >= 2560 && colt < 5632) {
;             const bool isk = colt >= 4096; const int cb0 = colt - (isk ? 4096 : 2560); const int grp = cb0 >> 9; const int gh = (cb0 >> 6) + wc;
;             const float* gp = (isk ? kg : qg) + grp * 64 + 8 * fq;
;             f32x4 gn[2][2];
; #pragma unroll
;             for (int bj = 0; bj < 2; ++bj)
; #pragma unroll
;                 for (int n = 0; n < 2; ++n) gn[bj][n] = *(const f32x4*)(gp + 32 * bj + 4 * n);
;             const float sc = isk ? 1.0f : qscale;
;             bf16_t* OB = isk ? KB : QB;
; #pragma unroll
;             for (int ai = 0; ai < 2; ++ai)
; #pragma unroll
;                 for (int m = 0; m < 4; ++m) { const int lrow = row0 + ai * HALF + m * 16; const int pos = lrow & 2047, bb = lrow >> 11;
;                     f32x4 y[2][2]; float ss = 0.f;
; #pragma unroll
;                     for (int bj = 0; bj < 2; ++bj)
; #pragma unroll
;                         for (int n = 0; n < 2; ++n) { y[bj][n] = acc[ai][bj][m][n]; ss += (y[bj][n][0] * y[bj][n][0] + y[bj][n][1] * y[bj][n][1]) + (y[bj][n][2] * y[bj][n][2] + y[bj][n][3] * y[bj][n][3]); }
;                     ss += __shfl_xor(ss, 16); ss += __shfl_xor(ss, 32);
;                     const float rs = __builtin_amdgcn_rsqf(ss * (1.0f / 64.0f) + 1e-6f);
; #pragma unroll
;                     for (int bj = 0; bj < 2; ++bj)
; #pragma unroll
;                         for (int n = 0; n < 2; ++n) y[bj][n] = y[bj][n] * gn[bj][n] * rs;
; #pragma unroll
;                     for (int n = 0; n < 2; ++n) { f32x4 pr;
; #pragma unroll
;                         for (int e = 0; e < 4; ++e) pr[e] = __shfl_xor(y[0][n][e], 16);
;                         if (fq < 2) { const f32x4 t0 = *(const f32x4*)(RT + (size_t)pos * 16 + 8 * n), t1 = *(const f32x4*)(RT + (size_t)pos * 16 + 8 * n + 4);
;                             const float co[4] = {t0[0], t0[2], t1[0], t1[2]}, si[4] = {t0[1], t0[3], t1[1], t1[3]};
; #pragma unroll
;                             for (int e = 0; e < 4; ++e) y[0][n][e] = (fq == 0) ? (y[0][n][e] * co[e] - pr[e] * si[e]) : (y[0][n][e] * co[e] + pr[e] * si[e]); } }
.LBB0_342:
	s_cmp_gt_u32 s74, 15
	s_cselect_b64 s[10:11], -1, 0
	s_and_b64 s[12:13], s[10:11], exec
	s_movk_i32 s12, 0xf600
	s_cselect_b32 s23, 0xfffff000, s12
	s_add_i32 s23, s23, s67
	s_ashr_i32 s40, s23, 9
	s_and_b64 s[12:13], s[10:11], exec
	s_cselect_b32 s41, s19, s17
	s_cselect_b32 s67, s18, s16
	s_lshl_b32 s12, s40, 6
	s_ashr_i32 s13, s12, 31
	s_lshl_b64 s[12:13], s[12:13], 2
	s_add_u32 s12, s67, s12
	s_addc_u32 s13, s41, s13
	global_load_dwordx4 v[142:145], v181, s[12:13] offset:16
	global_load_dwordx4 v[146:149], v181, s[12:13]
	global_load_dwordx4 v[134:137], v181, s[12:13] offset:144
	global_load_dwordx4 v[138:141], v181, s[12:13] offset:128
	v_and_b32_e32 v168, 64, v194
	v_xor_b32_e32 v167, 16, v194
	v_add_u32_e32 v168, 64, v168
	v_cmp_lt_i32_e32 vcc, v167, v168
	v_xor_b32_e32 v169, 32, v194
	v_pk_mul_f32 v[170:171], v[130:131], v[130:131]
	v_cndmask_b32_e32 v167, v194, v167, vcc
	v_cmp_lt_i32_e32 vcc, v169, v168
	v_lshlrev_b32_e32 v167, 2, v167
	s_waitcnt vmcnt(0)
	v_pk_mul_f32 v[130:131], v[130:131], v[146:147]
	v_cndmask_b32_e32 v168, v194, v169, vcc
	v_lshlrev_b32_e32 v183, 2, v168
	v_pk_mul_f32 v[168:169], v[132:133], v[132:133]
	v_pk_mul_f32 v[132:133], v[132:133], v[148:149]
	v_pk_mov_b32 v[172:173], v[170:171], v[168:169] op_sel:[1,0]
	v_mov_b32_e32 v171, v169
	v_pk_add_f32 v[168:169], v[172:173], v[170:171]
	v_pk_mul_f32 v[170:171], v[128:129], v[128:129]
	v_pk_mul_f32 v[172:173], v[126:127], v[126:127]
	v_pk_add_f32 v[168:169], v[168:169], v[168:169] op_sel:[0,1] op_sel_hi:[1,0]
	v_pk_mov_b32 v[174:175], v[172:173], v[170:171] op_sel:[1,0]
	v_mov_b32_e32 v173, v171
	v_pk_add_f32 v[170:171], v[174:175], v[172:173]
	v_mul_f32_e32 v172, v118, v118
	v_mul_f32_e32 v173, v119, v119
	v_pk_add_f32 v[170:171], v[170:171], v[170:171] op_sel:[0,1] op_sel_hi:[1,0]
	v_mov_b32_e32 v169, v172
	v_mov_b32_e32 v171, v173
	v_pk_add_f32 v[168:169], v[168:169], v[170:171]
	v_mul_f32_e32 v170, v123, v123
	v_mul_f32_e32 v172, v125, v125
	v_mul_f32_e32 v174, v120, v120
	v_mul_f32_e32 v175, v121, v121
	v_pk_fma_f32 v[170:171], v[122:123], v[122:123], v[170:171] op_sel_hi:[1,1,0]
	v_pk_fma_f32 v[172:173], v[124:125], v[124:125], v[172:173] op_sel_hi:[1,1,0]
	v_mov_b32_e32 v171, v174
	v_mov_b32_e32 v173, v175
	v_pk_add_f32 v[170:171], v[170:171], v[172:173]
	s_nop 0
	v_pk_add_f32 v[168:169], v[168:169], v[170:171]
	s_nop 0
	v_add_f32_e32 v168, v168, v169
	v_mov_b32_e32 v169, v168
	v_mov_b32_e32 v240, v168
	s_nop 1
	v_permlane16_swap_b32 v169, v240
	s_waitcnt lgkmcnt(0)
	v_add_f32_e32 v168, v169, v240
	v_mov_b32_e32 v169, v168
	v_mov_b32_e32 v240, v168
	s_nop 1
	v_permlane32_swap_b32 v169, v240
	s_waitcnt lgkmcnt(0)
	v_add_f32_e32 v168, v169, v240
	v_fmamk_f32 v168, v168, 0x3c800000, v188
	v_rsq_f32_e32 v170, v168
	s_nop 0
	v_pk_mul_f32 v[168:169], v[132:133], v[170:171] op_sel_hi:[1,0]
	v_pk_mul_f32 v[132:133], v[130:131], v[170:171] op_sel_hi:[1,0]
	ds_bpermute_b32 v174, v167, v132
	ds_bpermute_b32 v175, v167, v133
	ds_bpermute_b32 v172, v167, v168
	ds_bpermute_b32 v173, v167, v169
	v_lshlrev_b32_e32 v130, 6, v182
	v_mov_b32_e32 v131, v0
	v_lshl_add_u64 v[130:131], s[62:63], 0, v[130:131]
	v_mov_b32_e32 v252, v130
	v_mov_b32_e32 v253, v131
	v_mov_b32_e32 v248, 0x2000
	v_mov_b32_e32 v249, 0
	v_lshl_add_u64 v[250:251], v[130:131], 0, v[248:249]
	s_and_saveexec_b64 s[12:13], s[4:5]
	s_cbranch_execz .LBB0_344
	global_load_dwordx4 v[204:207], v[252:253], off
	global_load_dwordx4 v[208:211], v[252:253], off offset:16
	global_load_dwordx4 v[212:215], v[252:253], off offset:32
	global_load_dwordx4 v[216:219], v[252:253], off offset:48
	global_load_dwordx4 v[220:223], v[252:253], off offset:1024
	global_load_dwordx4 v[224:227], v[252:253], off offset:1040
	global_load_dwordx4 v[228:231], v[252:253], off offset:1056
	global_load_dwordx4 v[232:235], v[252:253], off offset:1072
	s_waitcnt vmcnt(4)
	v_mov_b32_e32 v184, v208
	v_mov_b32_e32 v185, v209
	v_mov_b32_e32 v186, v210
	v_mov_b32_e32 v187, v211
	v_mov_b32_e32 v200, v204
	v_mov_b32_e32 v201, v205
	v_mov_b32_e32 v202, v206
	v_mov_b32_e32 v203, v207
	v_mov_b32_e32 v177, v202
	v_mov_b32_e32 v202, v201
	s_waitcnt lgkmcnt(2)
	v_pk_mul_f32 v[174:175], v[202:203], v[174:175]
	v_mov_b32_e32 v176, v200
	v_cndmask_b32_e64 v175, v175, -v175, s[6:7]
	v_cndmask_b32_e64 v174, v174, -v174, s[6:7]
	v_pk_fma_f32 v[132:133], v[132:133], v[176:177], v[174:175]
	v_mov_b32_e32 v175, v186
	v_mov_b32_e32 v186, v185
	s_waitcnt lgkmcnt(0)
	v_pk_mul_f32 v[172:173], v[186:187], v[172:173]
	v_mov_b32_e32 v174, v184
	v_cndmask_b32_e64 v173, v173, -v173, s[6:7]
	v_cndmask_b32_e64 v172, v172, -v172, s[6:7]
	v_pk_fma_f32 v[168:169], v[168:169], v[174:175], v[172:173]

; __device__ __forceinline__ unsigned cvt_pk_bf16(float lo, float hi) { unsigned r; asm volatile("v_cvt_pk_bf16_f32 %0, %1, %2" : "=v"(r) : "v"(lo), "v"(hi)); return r; }
;     __device__ __forceinline__ static int permpos(int t, int g) { const int dsh = 2 * g; return (t & ((1 << dsh) - 1)) * (2048 >> dsh) + (t >> dsh); }
;     __device__ __forceinline__ void operator()(const f32x4 (&acc)[2][2][4][2], const Unit& u, int wr, int wc, int fr, int fq) const {
;     ...
;                 for (int m = 0; m < 4; ++m) { const int lrow = row0 + ai * HALF + m * 16; const int pos = lrow & 2047, bb = lrow >> 11;
;                     f32x4 y[2][2]; float ss = 0.f;
; #pragma unroll
;                     for (int bj = 0; bj < 2; ++bj)
; #pragma unroll
;                         for (int n = 0; n < 2; ++n) { y[bj][n] = acc[ai][bj][m][n]; ss += (y[bj][n][0] * y[bj][n][0] + y[bj][n][1] * y[bj][n][1]) + (y[bj][n][2] * y[bj][n][2] + y[bj][n][3] * y[bj][n][3]); }
;                     ss += __shfl_xor(ss, 16); ss += __shfl_xor(ss, 32);
;                     const float rs = __builtin_amdgcn_rsqf(ss * (1.0f / 64.0f) + 1e-6f);
; #pragma unroll
;                     for (int bj = 0; bj < 2; ++bj)
; #pragma unroll
;                         for (int n = 0; n < 2; ++n) y[bj][n] = y[bj][n] * gn[bj][n] * rs;
; #pragma unroll
;                     for (int n = 0; n < 2; ++n) { f32x4 pr;
; #pragma unroll
;                         for (int e = 0; e < 4; ++e) pr[e] = __shfl_xor(y[0][n][e], 16);
;                         if (fq < 2) { const f32x4 t0 = *(const f32x4*)(RT + (size_t)pos * 16 + 8 * n), t1 = *(const f32x4*)(RT + (size_t)pos * 16 + 8 * n + 4);
;                             const float co[4] = {t0[0], t0[2], t1[0], t1[2]}, si[4] = {t0[1], t0[3], t1[1], t1[3]};
; #pragma unroll
;                             for (int e = 0; e < 4; ++e) y[0][n][e] = (fq == 0) ? (y[0][n][e] * co[e] - pr[e] * si[e]) : (y[0][n][e] * co[e] + pr[e] * si[e]); } }
;                     bf16_t* rowp = OB + ((size_t)(bb * 24 + gh) * 2048 + permpos(pos, grp)) * 64 + 8 * fq;
; #pragma unroll
;                     for (int bj = 0; bj < 2; ++bj) { const f32x4 v0 = y[bj][0] * sc, v1 = y[bj][1] * sc;
;                         u32x4 w; w.x = cvt_pk_bf16(v0[0], v0[1]); w.y = cvt_pk_bf16(v0[2], v0[3]); w.z = cvt_pk_bf16(v1[0], v1[1]); w.w = cvt_pk_bf16(v1[2], v1[3]);
;                         *(u32x4*)(rowp + 32 * bj) = w; }
.LBB0_346:
	s_or_b64 exec, exec, s[12:13]
	s_ashr_i32 s12, s23, 6
	s_or_b32 s23, s12, s54
	s_waitcnt lgkmcnt(1)
	v_mov_b32_e32 v126, 0x3e38aa3b
	v_cndmask_b32_e64 v126, v126, 1.0, s[10:11]
	s_and_b64 s[10:11], s[10:11], exec
	s_cselect_b32 s11, s27, s82
	s_cselect_b32 s10, s26, s83
	v_lshl_add_u64 v[128:129], v[160:161], 0, s[10:11]
	s_ashr_i32 s10, s22, 11
	s_lshl_b32 s12, s40, 1
	s_mul_i32 s10, s10, 24
	s_lshl_b32 s40, -1, s12
	s_add_i32 s10, s23, s10
	v_pk_mul_f32 v[122:123], v[122:123], v[138:139]
	v_pk_mul_f32 v[118:119], v[118:119], v[134:135]
	s_lshr_b32 s13, 0x800, s12
	s_ashr_i32 s11, s10, 31
	v_pk_mul_f32 v[122:123], v[122:123], v[170:171]
	v_pk_mul_f32 v[170:171], v[118:119], v[170:171]
	v_bitop3_b32 v118, v182, s40, v182 bitop3:0x30
	s_lshl_b64 s[10:11], s[10:11], 18
	v_mul_u32_u24_e32 v118, s13, v118
	v_lshrrev_b32_e32 v119, s12, v182
	v_lshl_add_u64 v[130:131], v[128:129], 0, s[10:11]
	v_pk_mul_f32 v[124:125], v[124:125], v[140:141]
	v_pk_mul_f32 v[120:121], v[120:121], v[136:137]
	v_add_lshl_u32 v118, v118, v119, 7
	v_mov_b32_e32 v119, v0
	v_pk_mul_f32 v[124:125], v[124:125], v[176:177]
	v_pk_mul_f32 v[176:177], v[120:121], v[176:177]
	v_lshl_add_u64 v[184:185], v[130:131], 0, v[118:119]
	s_waitcnt lgkmcnt(0)
	v_pk_mul_f32 v[120:121], v[126:127], v[168:169] op_sel_hi:[0,1]
	v_pk_mul_f32 v[118:119], v[126:127], v[132:133] op_sel_hi:[0,1]
	v_pk_mul_f32 v[132:133], v[126:127], v[174:175] op_sel_hi:[0,1]
	v_pk_mul_f32 v[168:169], v[126:127], v[172:173] op_sel_hi:[0,1]
	v_cvt_pk_bf16_f32 v118, v118, v119
	v_cvt_pk_bf16_f32 v119, v120, v121
	v_cvt_pk_bf16_f32 v120, v168, v169
	v_cvt_pk_bf16_f32 v121, v132, v133
	global_store_dwordx4 v[184:185], v[118:121], off
	s_nop 1
	v_pk_mul_f32 v[120:121], v[126:127], v[124:125] op_sel_hi:[0,1]
	v_pk_mul_f32 v[118:119], v[116:117], v[116:117]
	v_pk_mul_f32 v[124:125], v[114:115], v[114:115]
	v_mul_f32_e32 v127, v102, v102
	v_pk_mov_b32 v[132:133], v[124:125], v[118:119] op_sel:[1,0]
	v_mov_b32_e32 v125, v119
	v_pk_add_f32 v[118:119], v[132:133], v[124:125]
	v_pk_mul_f32 v[124:125], v[112:113], v[112:113]
	v_pk_mul_f32 v[132:133], v[110:111], v[110:111]
	v_pk_add_f32 v[118:119], v[118:119], v[118:119] op_sel:[0,1] op_sel_hi:[1,0]
	v_pk_mov_b32 v[168:169], v[132:133], v[124:125] op_sel:[1,0]
	v_mov_b32_e32 v133, v125
	v_pk_add_f32 v[124:125], v[168:169], v[132:133]
	v_mul_f32_e32 v132, v103, v103
	v_pk_add_f32 v[124:125], v[124:125], v[124:125] op_sel:[0,1] op_sel_hi:[1,0]
	v_mov_b32_e32 v119, v127
	v_mov_b32_e32 v125, v132
	v_pk_add_f32 v[118:119], v[118:119], v[124:125]
	v_mul_f32_e32 v124, v107, v107
	v_mul_f32_e32 v133, v104, v104
	v_pk_fma_f32 v[124:125], v[106:107], v[106:107], v[124:125] op_sel_hi:[1,1,0]
	v_mul_f32_e32 v132, v109, v109
	v_mul_f32_e32 v168, v105, v105
	v_mov_b32_e32 v125, v133
	v_pk_fma_f32 v[132:133], v[108:109], v[108:109], v[132:133] op_sel_hi:[1,1,0]
	v_pk_mul_f32 v[116:117], v[116:117], v[148:149]
	v_mov_b32_e32 v133, v168
	v_pk_add_f32 v[124:125], v[124:125], v[132:133]
	v_pk_mul_f32 v[114:115], v[114:115], v[146:147]
	v_pk_add_f32 v[118:119], v[118:119], v[124:125]
	v_or_b32_e32 v168, 16, v182
	v_add_f32_e32 v127, v118, v119
	v_mov_b32_e32 v132, v127
	v_mov_b32_e32 v240, v127
	s_nop 1
	v_permlane16_swap_b32 v132, v240
	v_pk_mul_f32 v[118:119], v[126:127], v[122:123] op_sel_hi:[0,1]
	v_pk_mul_f32 v[122:123], v[126:127], v[176:177] op_sel_hi:[0,1]
	v_pk_mul_f32 v[124:125], v[126:127], v[170:171] op_sel_hi:[0,1]
	v_cvt_pk_bf16_f32 v118, v118, v119
	s_waitcnt lgkmcnt(0)
	v_add_f32_e32 v127, v132, v240
	v_mov_b32_e32 v132, v127
	v_mov_b32_e32 v240, v127
	s_nop 1
	v_permlane32_swap_b32 v132, v240
	v_cvt_pk_bf16_f32 v119, v120, v121
	v_cvt_pk_bf16_f32 v120, v124, v125
	v_cvt_pk_bf16_f32 v121, v122, v123
	global_store_dwordx4 v[184:185], v[118:121], off offset:64
	s_waitcnt lgkmcnt(0)
	s_nop 0
	v_add_f32_e32 v118, v132, v240
	v_fmamk_f32 v118, v118, 0x3c800000, v188
	v_rsq_f32_e32 v118, v118
	v_lshlrev_b32_e32 v120, 6, v168
	v_mov_b32_e32 v121, v0
	v_lshl_add_u64 v[120:121], s[62:63], 0, v[120:121]
	v_pk_mul_f32 v[116:117], v[116:117], v[118:119] op_sel_hi:[1,0]
	v_pk_mul_f32 v[114:115], v[114:115], v[118:119] op_sel_hi:[1,0]
	ds_bpermute_b32 v124, v167, v114
	ds_bpermute_b32 v125, v167, v115
	ds_bpermute_b32 v122, v167, v116
	ds_bpermute_b32 v123, v167, v117
	s_and_saveexec_b64 s[10:11], s[4:5]
	s_cbranch_execz .LBB0_348
	global_load_dwordx4 v[204:207], v[252:253], off offset:2048
	global_load_dwordx4 v[208:211], v[252:253], off offset:2064
	global_load_dwordx4 v[212:215], v[252:253], off offset:2080
	global_load_dwordx4 v[216:219], v[252:253], off offset:2096
	s_waitcnt vmcnt(6)
	v_mov_b32_e32 v170, v224
	v_mov_b32_e32 v171, v225
	v_mov_b32_e32 v172, v226
	v_mov_b32_e32 v173, v227
	v_mov_b32_e32 v174, v220
	v_mov_b32_e32 v175, v221
	v_mov_b32_e32 v176, v222
	v_mov_b32_e32 v177, v223
	v_mov_b32_e32 v133, v176
	v_mov_b32_e32 v176, v175
	s_waitcnt lgkmcnt(2)
	v_pk_mul_f32 v[124:125], v[176:177], v[124:125]
	v_mov_b32_e32 v132, v174
	v_cndmask_b32_e64 v125, v125, -v125, s[6:7]
	v_cndmask_b32_e64 v124, v124, -v124, s[6:7]
	v_pk_fma_f32 v[114:115], v[114:115], v[132:133], v[124:125]
	v_mov_b32_e32 v125, v172
	v_mov_b32_e32 v172, v171
	s_waitcnt lgkmcnt(0)
	v_pk_mul_f32 v[122:123], v[172:173], v[122:123]
	v_mov_b32_e32 v124, v170
	v_cndmask_b32_e64 v123, v123, -v123, s[6:7]
	v_cndmask_b32_e64 v122, v122, -v122, s[6:7]
	v_pk_fma_f32 v[116:117], v[116:117], v[124:125], v[122:123]

; __device__ __forceinline__ unsigned cvt_pk_bf16(float lo, float hi) { unsigned r; asm volatile("v_cvt_pk_bf16_f32 %0, %1, %2" : "=v"(r) : "v"(lo), "v"(hi)); return r; }
;     __device__ __forceinline__ static int permpos(int t, int g) { const int dsh = 2 * g; return (t & ((1 << dsh) - 1)) * (2048 >> dsh) + (t >> dsh); }
;     __device__ __forceinline__ void operator()(const f32x4 (&acc)[2][2][4][2], const Unit& u, int wr, int wc, int fr, int fq) const {
;     ...
;                 for (int m = 0; m < 4; ++m) { const int lrow = row0 + ai * HALF + m * 16; const int pos = lrow & 2047, bb = lrow >> 11;
;                     f32x4 y[2][2]; float ss = 0.f;
; #pragma unroll
;                     for (int bj = 0; bj < 2; ++bj)
; #pragma unroll
;                         for (int n = 0; n < 2; ++n) { y[bj][n] = acc[ai][bj][m][n]; ss += (y[bj][n][0] * y[bj][n][0] + y[bj][n][1] * y[bj][n][1]) + (y[bj][n][2] * y[bj][n][2] + y[bj][n][3] * y[bj][n][3]); }
;                     ss += __shfl_xor(ss, 16); ss += __shfl_xor(ss, 32);
;                     const float rs = __builtin_amdgcn_rsqf(ss * (1.0f / 64.0f) + 1e-6f);
; #pragma unroll
;                     for (int bj = 0; bj < 2; ++bj)
; #pragma unroll
;                         for (int n = 0; n < 2; ++n) y[bj][n] = y[bj][n] * gn[bj][n] * rs;
; #pragma unroll
;                     for (int n = 0; n < 2; ++n) { f32x4 pr;
; #pragma unroll
;                         for (int e = 0; e < 4; ++e) pr[e] = __shfl_xor(y[0][n][e], 16);
;                         if (fq < 2) { const f32x4 t0 = *(const f32x4*)(RT + (size_t)pos * 16 + 8 * n), t1 = *(const f32x4*)(RT + (size_t)pos * 16 + 8 * n + 4);
;                             const float co[4] = {t0[0], t0[2], t1[0], t1[2]}, si[4] = {t0[1], t0[3], t1[1], t1[3]};
; #pragma unroll
;                             for (int e = 0; e < 4; ++e) y[0][n][e] = (fq == 0) ? (y[0][n][e] * co[e] - pr[e] * si[e]) : (y[0][n][e] * co[e] + pr[e] * si[e]); } }
;                     bf16_t* rowp = OB + ((size_t)(bb * 24 + gh) * 2048 + permpos(pos, grp)) * 64 + 8 * fq;
; #pragma unroll
;                     for (int bj = 0; bj < 2; ++bj) { const f32x4 v0 = y[bj][0] * sc, v1 = y[bj][1] * sc;
;                         u32x4 w; w.x = cvt_pk_bf16(v0[0], v0[1]); w.y = cvt_pk_bf16(v0[2], v0[3]); w.z = cvt_pk_bf16(v1[0], v1[1]); w.w = cvt_pk_bf16(v1[2], v1[3]);
;                         *(u32x4*)(rowp + 32 * bj) = w; }
.LBB0_350:
	s_or_b64 exec, exec, s[10:11]
	s_not_b32 s22, s40
	v_pk_mul_f32 v[106:107], v[106:107], v[138:139]
	v_pk_mul_f32 v[102:103], v[102:103], v[134:135]
	v_pk_mul_f32 v[106:107], v[106:107], v[118:119]
	v_pk_mul_f32 v[118:119], v[102:103], v[118:119]
	v_and_b32_e32 v102, s22, v168
	v_mul_u32_u24_e32 v102, s13, v102
	v_lshrrev_b32_e32 v103, s12, v168
	v_mov_b32_e32 v127, v126
	v_pk_mul_f32 v[108:109], v[108:109], v[140:141]
	v_pk_mul_f32 v[104:105], v[104:105], v[136:137]
	v_add_lshl_u32 v102, v102, v103, 7
	v_mov_b32_e32 v103, v0
	s_waitcnt lgkmcnt(1)
	v_mov_b32_e32 v124, v126
	s_waitcnt lgkmcnt(0)
	v_mov_b32_e32 v125, v126
	v_pk_mul_f32 v[108:109], v[108:109], v[122:123]
	v_pk_mul_f32 v[120:121], v[104:105], v[122:123]
	v_lshl_add_u64 v[122:123], v[130:131], 0, v[102:103]
	v_pk_mul_f32 v[104:105], v[124:125], v[116:117]
	v_pk_mul_f32 v[102:103], v[126:127], v[114:115]
	v_pk_mul_f32 v[112:113], v[124:125], v[112:113]
	v_pk_mul_f32 v[110:111], v[126:127], v[110:111]
	v_cvt_pk_bf16_f32 v102, v102, v103
	v_cvt_pk_bf16_f32 v103, v104, v105
	s_nop 0
	v_cvt_pk_bf16_f32 v104, v110, v111
	v_cvt_pk_bf16_f32 v105, v112, v113
	global_store_dwordx4 v[122:123], v[102:105], off
	s_nop 1
	v_pk_mul_f32 v[104:105], v[124:125], v[108:109]
	v_pk_mul_f32 v[102:103], v[100:101], v[100:101]
	v_pk_mul_f32 v[108:109], v[98:99], v[98:99]
	v_pk_mul_f32 v[100:101], v[100:101], v[148:149]
	v_pk_mov_b32 v[110:111], v[108:109], v[102:103] op_sel:[1,0]
	v_mov_b32_e32 v109, v103
	v_pk_add_f32 v[102:103], v[110:111], v[108:109]
	v_pk_mul_f32 v[108:109], v[96:97], v[96:97]
	v_pk_mul_f32 v[110:111], v[94:95], v[94:95]
	v_pk_add_f32 v[102:103], v[102:103], v[102:103] op_sel:[0,1] op_sel_hi:[1,0]
	v_pk_mov_b32 v[112:113], v[110:111], v[108:109] op_sel:[1,0]
	v_mov_b32_e32 v111, v109
	v_pk_add_f32 v[108:109], v[112:113], v[110:111]
	v_mul_f32_e32 v110, v86, v86
	v_mul_f32_e32 v111, v87, v87
	v_pk_add_f32 v[108:109], v[108:109], v[108:109] op_sel:[0,1] op_sel_hi:[1,0]
	v_mov_b32_e32 v103, v110
	v_mov_b32_e32 v109, v111
	v_pk_add_f32 v[102:103], v[102:103], v[108:109]
	v_mul_f32_e32 v108, v91, v91
	v_mul_f32_e32 v110, v93, v93
	v_mul_f32_e32 v112, v88, v88
	v_mul_f32_e32 v113, v89, v89
	v_pk_fma_f32 v[108:109], v[90:91], v[90:91], v[108:109] op_sel_hi:[1,1,0]
	v_pk_fma_f32 v[110:111], v[92:93], v[92:93], v[110:111] op_sel_hi:[1,1,0]
	v_mov_b32_e32 v109, v112
	v_mov_b32_e32 v111, v113
	v_pk_add_f32 v[108:109], v[108:109], v[110:111]
	v_pk_mul_f32 v[98:99], v[98:99], v[146:147]
	v_pk_add_f32 v[102:103], v[102:103], v[108:109]
	v_pk_mul_f32 v[108:109], v[126:127], v[118:119]
	v_add_f32_e32 v110, v102, v103
	v_mov_b32_e32 v111, v110
	v_mov_b32_e32 v240, v110
	s_nop 1
	v_permlane16_swap_b32 v111, v240
	v_pk_mul_f32 v[102:103], v[126:127], v[106:107]
	v_pk_mul_f32 v[106:107], v[124:125], v[120:121]
	v_cvt_pk_bf16_f32 v102, v102, v103
	v_cvt_pk_bf16_f32 v103, v104, v105
	s_waitcnt lgkmcnt(0)
	v_add_f32_e32 v110, v111, v240
	v_mov_b32_e32 v111, v110
	v_mov_b32_e32 v240, v110
	s_nop 1
	v_permlane32_swap_b32 v111, v240
	v_cvt_pk_bf16_f32 v104, v108, v109
	v_cvt_pk_bf16_f32 v105, v106, v107
	global_store_dwordx4 v[122:123], v[102:105], off offset:64
	v_or_b32_e32 v112, 32, v182
	s_waitcnt lgkmcnt(0)
	v_add_f32_e32 v102, v111, v240
	v_fmamk_f32 v102, v102, 0x3c800000, v188
	v_rsq_f32_e32 v102, v102
	v_lshlrev_b32_e32 v104, 6, v112
	v_mov_b32_e32 v105, v0
	v_lshl_add_u64 v[104:105], s[62:63], 0, v[104:105]
	v_pk_mul_f32 v[100:101], v[100:101], v[102:103] op_sel_hi:[1,0]
	v_pk_mul_f32 v[98:99], v[98:99], v[102:103] op_sel_hi:[1,0]
	ds_bpermute_b32 v108, v167, v98
	ds_bpermute_b32 v109, v167, v99
	ds_bpermute_b32 v106, v167, v100
	ds_bpermute_b32 v107, v167, v101
	s_and_saveexec_b64 s[10:11], s[4:5]
	s_cbranch_execz .LBB0_352
	global_load_dwordx4 v[220:223], v[252:253], off offset:3072
	global_load_dwordx4 v[224:227], v[252:253], off offset:3088
	global_load_dwordx4 v[228:231], v[252:253], off offset:3104
	global_load_dwordx4 v[232:235], v[252:253], off offset:3120
	s_waitcnt vmcnt(6)
	v_mov_b32_e32 v114, v208
	v_mov_b32_e32 v115, v209
	v_mov_b32_e32 v116, v210
	v_mov_b32_e32 v117, v211
	v_mov_b32_e32 v118, v204
	v_mov_b32_e32 v119, v205
	v_mov_b32_e32 v120, v206
	v_mov_b32_e32 v121, v207
	v_mov_b32_e32 v111, v120
	v_mov_b32_e32 v120, v119
	s_waitcnt lgkmcnt(2)
	v_pk_mul_f32 v[108:109], v[120:121], v[108:109]
	v_mov_b32_e32 v110, v118
	v_cndmask_b32_e64 v109, v109, -v109, s[6:7]
	v_cndmask_b32_e64 v108, v108, -v108, s[6:7]
	v_pk_fma_f32 v[98:99], v[98:99], v[110:111], v[108:109]
	v_mov_b32_e32 v109, v116
	v_mov_b32_e32 v116, v115
	s_waitcnt lgkmcnt(0)
	v_pk_mul_f32 v[106:107], v[116:117], v[106:107]
	v_mov_b32_e32 v108, v114
	v_cndmask_b32_e64 v107, v107, -v107, s[6:7]
	v_cndmask_b32_e64 v106, v106, -v106, s[6:7]
	v_pk_fma_f32 v[100:101], v[100:101], v[108:109], v[106:107]

; __device__ __forceinline__ unsigned cvt_pk_bf16(float lo, float hi) { unsigned r; asm volatile("v_cvt_pk_bf16_f32 %0, %1, %2" : "=v"(r) : "v"(lo), "v"(hi)); return r; }
;     __device__ __forceinline__ static int permpos(int t, int g) { const int dsh = 2 * g; return (t & ((1 << dsh) - 1)) * (2048 >> dsh) + (t >> dsh); }
;     __device__ __forceinline__ void operator()(const f32x4 (&acc)[2][2][4][2], const Unit& u, int wr, int wc, int fr, int fq) const {
;     ...
;                 for (int m = 0; m < 4; ++m) { const int lrow = row0 + ai * HALF + m * 16; const int pos = lrow & 2047, bb = lrow >> 11;
;                     f32x4 y[2][2]; float ss = 0.f;
; #pragma unroll
;                     for (int bj = 0; bj < 2; ++bj)
; #pragma unroll
;                         for (int n = 0; n < 2; ++n) { y[bj][n] = acc[ai][bj][m][n]; ss += (y[bj][n][0] * y[bj][n][0] + y[bj][n][1] * y[bj][n][1]) + (y[bj][n][2] * y[bj][n][2] + y[bj][n][3] * y[bj][n][3]); }
;                     ss += __shfl_xor(ss, 16); ss += __shfl_xor(ss, 32);
;                     const float rs = __builtin_amdgcn_rsqf(ss * (1.0f / 64.0f) + 1e-6f);
; #pragma unroll
;                     for (int bj = 0; bj < 2; ++bj)
; #pragma unroll
;                         for (int n = 0; n < 2; ++n) y[bj][n] = y[bj][n] * gn[bj][n] * rs;
; #pragma unroll
;                     for (int n = 0; n < 2; ++n) { f32x4 pr;
; #pragma unroll
;                         for (int e = 0; e < 4; ++e) pr[e] = __shfl_xor(y[0][n][e], 16);
;                         if (fq < 2) { const f32x4 t0 = *(const f32x4*)(RT + (size_t)pos * 16 + 8 * n), t1 = *(const f32x4*)(RT + (size_t)pos * 16 + 8 * n + 4);
;                             const float co[4] = {t0[0], t0[2], t1[0], t1[2]}, si[4] = {t0[1], t0[3], t1[1], t1[3]};
; #pragma unroll
;                             for (int e = 0; e < 4; ++e) y[0][n][e] = (fq == 0) ? (y[0][n][e] * co[e] - pr[e] * si[e]) : (y[0][n][e] * co[e] + pr[e] * si[e]); } }
;                     bf16_t* rowp = OB + ((size_t)(bb * 24 + gh) * 2048 + permpos(pos, grp)) * 64 + 8 * fq;
; #pragma unroll
;                     for (int bj = 0; bj < 2; ++bj) { const f32x4 v0 = y[bj][0] * sc, v1 = y[bj][1] * sc;
;                         u32x4 w; w.x = cvt_pk_bf16(v0[0], v0[1]); w.y = cvt_pk_bf16(v0[2], v0[3]); w.z = cvt_pk_bf16(v1[0], v1[1]); w.w = cvt_pk_bf16(v1[2], v1[3]);
;                         *(u32x4*)(rowp + 32 * bj) = w; }
.LBB0_354:
	s_or_b64 exec, exec, s[10:11]
	v_pk_mul_f32 v[90:91], v[90:91], v[138:139]
	v_pk_mul_f32 v[86:87], v[86:87], v[134:135]
	v_pk_mul_f32 v[90:91], v[90:91], v[102:103]
	v_pk_mul_f32 v[102:103], v[86:87], v[102:103]
	v_and_b32_e32 v86, s22, v112
	v_mul_u32_u24_e32 v86, s13, v86
	v_lshrrev_b32_e32 v87, s12, v112
	v_pk_mul_f32 v[92:93], v[92:93], v[140:141]
	v_pk_mul_f32 v[88:89], v[88:89], v[136:137]
	v_add_lshl_u32 v86, v86, v87, 7
	v_mov_b32_e32 v87, v0
	s_waitcnt lgkmcnt(1)
	v_mov_b32_e32 v108, v126
	s_waitcnt lgkmcnt(0)
	v_mov_b32_e32 v109, v126
	v_pk_mul_f32 v[92:93], v[92:93], v[106:107]
	v_pk_mul_f32 v[104:105], v[88:89], v[106:107]
	v_lshl_add_u64 v[106:107], v[130:131], 0, v[86:87]
	v_pk_mul_f32 v[88:89], v[108:109], v[100:101]
	v_pk_mul_f32 v[86:87], v[126:127], v[98:99]
	v_pk_mul_f32 v[96:97], v[108:109], v[96:97]
	v_pk_mul_f32 v[94:95], v[126:127], v[94:95]
	v_cvt_pk_bf16_f32 v86, v86, v87
	v_cvt_pk_bf16_f32 v87, v88, v89
	s_nop 0
	v_cvt_pk_bf16_f32 v88, v94, v95
	v_cvt_pk_bf16_f32 v89, v96, v97
	global_store_dwordx4 v[106:107], v[86:89], off
	s_nop 1
	v_pk_mul_f32 v[88:89], v[108:109], v[92:93]
	v_pk_mul_f32 v[86:87], v[80:81], v[80:81]
	v_pk_mul_f32 v[92:93], v[78:79], v[78:79]
	v_pk_mul_f32 v[80:81], v[80:81], v[148:149]
	v_pk_mov_b32 v[94:95], v[92:93], v[86:87] op_sel:[1,0]
	v_mov_b32_e32 v93, v87
	v_pk_add_f32 v[86:87], v[94:95], v[92:93]
	v_pk_mul_f32 v[92:93], v[76:77], v[76:77]
	v_pk_mul_f32 v[94:95], v[74:75], v[74:75]
	v_pk_add_f32 v[86:87], v[86:87], v[86:87] op_sel:[0,1] op_sel_hi:[1,0]
	v_pk_mov_b32 v[96:97], v[94:95], v[92:93] op_sel:[1,0]
	v_mov_b32_e32 v95, v93
	v_pk_add_f32 v[92:93], v[96:97], v[94:95]
	v_mul_f32_e32 v94, v66, v66
	v_mul_f32_e32 v95, v67, v67
	v_pk_add_f32 v[92:93], v[92:93], v[92:93] op_sel:[0,1] op_sel_hi:[1,0]
	v_mov_b32_e32 v87, v94
	v_mov_b32_e32 v93, v95
	v_pk_add_f32 v[86:87], v[86:87], v[92:93]
	v_mul_f32_e32 v92, v71, v71
	v_mul_f32_e32 v94, v73, v73
	v_mul_f32_e32 v96, v68, v68
	v_mul_f32_e32 v97, v69, v69
	v_pk_fma_f32 v[92:93], v[70:71], v[70:71], v[92:93] op_sel_hi:[1,1,0]
	v_pk_fma_f32 v[94:95], v[72:73], v[72:73], v[94:95] op_sel_hi:[1,1,0]
	v_mov_b32_e32 v93, v96
	v_mov_b32_e32 v95, v97
	v_pk_add_f32 v[92:93], v[92:93], v[94:95]
	v_pk_mul_f32 v[78:79], v[78:79], v[146:147]
	v_pk_add_f32 v[86:87], v[86:87], v[92:93]
	v_pk_mul_f32 v[92:93], v[126:127], v[102:103]
	v_add_f32_e32 v94, v86, v87
	v_mov_b32_e32 v95, v94
	v_mov_b32_e32 v240, v94
	s_nop 1
	v_permlane16_swap_b32 v95, v240
	v_pk_mul_f32 v[86:87], v[126:127], v[90:91]
	v_pk_mul_f32 v[90:91], v[108:109], v[104:105]
	v_cvt_pk_bf16_f32 v86, v86, v87
	v_cvt_pk_bf16_f32 v87, v88, v89
	s_waitcnt lgkmcnt(0)
	v_add_f32_e32 v94, v95, v240
	v_mov_b32_e32 v95, v94
	v_mov_b32_e32 v240, v94
	s_nop 1
	v_permlane32_swap_b32 v95, v240
	v_cvt_pk_bf16_f32 v88, v92, v93
	v_cvt_pk_bf16_f32 v89, v90, v91
	global_store_dwordx4 v[106:107], v[86:89], off offset:64
	v_or_b32_e32 v96, 48, v182
	s_waitcnt lgkmcnt(0)
	v_add_f32_e32 v86, v95, v240
	v_fmamk_f32 v86, v86, 0x3c800000, v188
	v_rsq_f32_e32 v86, v86
	v_lshlrev_b32_e32 v88, 6, v96
	v_mov_b32_e32 v89, v0
	v_lshl_add_u64 v[88:89], s[62:63], 0, v[88:89]
	v_pk_mul_f32 v[80:81], v[80:81], v[86:87] op_sel_hi:[1,0]
	v_pk_mul_f32 v[78:79], v[78:79], v[86:87] op_sel_hi:[1,0]
	ds_bpermute_b32 v92, v167, v78
	ds_bpermute_b32 v93, v167, v79
	ds_bpermute_b32 v90, v167, v80
	ds_bpermute_b32 v91, v167, v81
	s_and_saveexec_b64 s[10:11], s[4:5]
	s_cbranch_execz .LBB0_356
	global_load_dwordx4 v[204:207], v[250:251], off
	global_load_dwordx4 v[208:211], v[250:251], off offset:16
	global_load_dwordx4 v[212:215], v[250:251], off offset:32
	global_load_dwordx4 v[216:219], v[250:251], off offset:48
	s_waitcnt vmcnt(6)
	v_mov_b32_e32 v98, v224
	v_mov_b32_e32 v99, v225
	v_mov_b32_e32 v100, v226
	v_mov_b32_e32 v101, v227
	v_mov_b32_e32 v102, v220
	v_mov_b32_e32 v103, v221
	v_mov_b32_e32 v104, v222
	v_mov_b32_e32 v105, v223
	v_mov_b32_e32 v95, v104
	v_mov_b32_e32 v104, v103
	s_waitcnt lgkmcnt(2)
	v_pk_mul_f32 v[92:93], v[104:105], v[92:93]
	v_mov_b32_e32 v94, v102
	v_cndmask_b32_e64 v93, v93, -v93, s[6:7]
	v_cndmask_b32_e64 v92, v92, -v92, s[6:7]
	v_pk_fma_f32 v[78:79], v[78:79], v[94:95], v[92:93]
	v_mov_b32_e32 v93, v100
	v_mov_b32_e32 v100, v99
	s_waitcnt lgkmcnt(0)
	v_pk_mul_f32 v[90:91], v[100:101], v[90:91]
	v_mov_b32_e32 v92, v98
	v_cndmask_b32_e64 v91, v91, -v91, s[6:7]
	v_cndmask_b32_e64 v90, v90, -v90, s[6:7]
	v_pk_fma_f32 v[80:81], v[80:81], v[92:93], v[90:91]

; __device__ __forceinline__ unsigned cvt_pk_bf16(float lo, float hi) { unsigned r; asm volatile("v_cvt_pk_bf16_f32 %0, %1, %2" : "=v"(r) : "v"(lo), "v"(hi)); return r; }
;     __device__ __forceinline__ static int permpos(int t, int g) { const int dsh = 2 * g; return (t & ((1 << dsh) - 1)) * (2048 >> dsh) + (t >> dsh); }
;     __device__ __forceinline__ void operator()(const f32x4 (&acc)[2][2][4][2], const Unit& u, int wr, int wc, int fr, int fq) const {
;     ...
;                 for (int m = 0; m < 4; ++m) { const int lrow = row0 + ai * HALF + m * 16; const int pos = lrow & 2047, bb = lrow >> 11;
;                     f32x4 y[2][2]; float ss = 0.f;
; #pragma unroll
;                     for (int bj = 0; bj < 2; ++bj)
; #pragma unroll
;                         for (int n = 0; n < 2; ++n) { y[bj][n] = acc[ai][bj][m][n]; ss += (y[bj][n][0] * y[bj][n][0] + y[bj][n][1] * y[bj][n][1]) + (y[bj][n][2] * y[bj][n][2] + y[bj][n][3] * y[bj][n][3]); }
;                     ss += __shfl_xor(ss, 16); ss += __shfl_xor(ss, 32);
;                     const float rs = __builtin_amdgcn_rsqf(ss * (1.0f / 64.0f) + 1e-6f);
; #pragma unroll
;                     for (int bj = 0; bj < 2; ++bj)
; #pragma unroll
;                         for (int n = 0; n < 2; ++n) y[bj][n] = y[bj][n] * gn[bj][n] * rs;
; #pragma unroll
;                     for (int n = 0; n < 2; ++n) { f32x4 pr;
; #pragma unroll
;                         for (int e = 0; e < 4; ++e) pr[e] = __shfl_xor(y[0][n][e], 16);
;                         if (fq < 2) { const f32x4 t0 = *(const f32x4*)(RT + (size_t)pos * 16 + 8 * n), t1 = *(const f32x4*)(RT + (size_t)pos * 16 + 8 * n + 4);
;                             const float co[4] = {t0[0], t0[2], t1[0], t1[2]}, si[4] = {t0[1], t0[3], t1[1], t1[3]};
; #pragma unroll
;                             for (int e = 0; e < 4; ++e) y[0][n][e] = (fq == 0) ? (y[0][n][e] * co[e] - pr[e] * si[e]) : (y[0][n][e] * co[e] + pr[e] * si[e]); } }
;                     bf16_t* rowp = OB + ((size_t)(bb * 24 + gh) * 2048 + permpos(pos, grp)) * 64 + 8 * fq;
; #pragma unroll
;                     for (int bj = 0; bj < 2; ++bj) { const f32x4 v0 = y[bj][0] * sc, v1 = y[bj][1] * sc;
;                         u32x4 w; w.x = cvt_pk_bf16(v0[0], v0[1]); w.y = cvt_pk_bf16(v0[2], v0[3]); w.z = cvt_pk_bf16(v1[0], v1[1]); w.w = cvt_pk_bf16(v1[2], v1[3]);
;                         *(u32x4*)(rowp + 32 * bj) = w; }
.LBB0_358:
	s_or_b64 exec, exec, s[10:11]
	v_pk_mul_f32 v[70:71], v[70:71], v[138:139]
	v_pk_mul_f32 v[66:67], v[66:67], v[134:135]
	v_pk_mul_f32 v[70:71], v[70:71], v[86:87]
	v_pk_mul_f32 v[86:87], v[66:67], v[86:87]
	v_and_b32_e32 v66, s22, v96
	v_mul_u32_u24_e32 v66, s13, v66
	v_lshrrev_b32_e32 v67, s12, v96
	v_pk_mul_f32 v[72:73], v[72:73], v[140:141]
	v_pk_mul_f32 v[68:69], v[68:69], v[136:137]
	v_add_lshl_u32 v66, v66, v67, 7
	v_mov_b32_e32 v67, v0
	s_waitcnt lgkmcnt(1)
	v_mov_b32_e32 v92, v126
	s_waitcnt lgkmcnt(0)
	v_mov_b32_e32 v93, v126
	v_pk_mul_f32 v[72:73], v[72:73], v[90:91]
	v_pk_mul_f32 v[88:89], v[68:69], v[90:91]
	v_lshl_add_u64 v[90:91], v[130:131], 0, v[66:67]
	v_pk_mul_f32 v[68:69], v[92:93], v[80:81]
	v_pk_mul_f32 v[66:67], v[126:127], v[78:79]
	v_pk_mul_f32 v[76:77], v[92:93], v[76:77]
	v_pk_mul_f32 v[74:75], v[126:127], v[74:75]
	v_cvt_pk_bf16_f32 v66, v66, v67
	v_cvt_pk_bf16_f32 v67, v68, v69
	s_nop 0
	v_cvt_pk_bf16_f32 v68, v74, v75
	v_cvt_pk_bf16_f32 v69, v76, v77
	global_store_dwordx4 v[90:91], v[66:69], off
	s_nop 1
	v_pk_mul_f32 v[68:69], v[92:93], v[72:73]
	v_pk_mul_f32 v[66:67], v[126:127], v[70:71]
	v_pk_mul_f32 v[70:71], v[64:65], v[64:65]
	v_pk_mul_f32 v[72:73], v[62:63], v[62:63]
	v_cvt_pk_bf16_f32 v66, v66, v67
	v_cvt_pk_bf16_f32 v67, v68, v69
	v_pk_mul_f32 v[64:65], v[64:65], v[148:149]
	v_pk_mov_b32 v[74:75], v[72:73], v[70:71] op_sel:[1,0]
	v_mov_b32_e32 v73, v71
	v_pk_add_f32 v[70:71], v[74:75], v[72:73]
	v_pk_mul_f32 v[72:73], v[60:61], v[60:61]
	v_pk_mul_f32 v[74:75], v[58:59], v[58:59]
	v_pk_add_f32 v[70:71], v[70:71], v[70:71] op_sel:[0,1] op_sel_hi:[1,0]
	v_pk_mov_b32 v[76:77], v[74:75], v[72:73] op_sel:[1,0]
	v_mov_b32_e32 v75, v73
	v_pk_add_f32 v[72:73], v[76:77], v[74:75]
	v_mul_f32_e32 v74, v50, v50
	v_mul_f32_e32 v75, v51, v51
	v_pk_add_f32 v[72:73], v[72:73], v[72:73] op_sel:[0,1] op_sel_hi:[1,0]
	v_mov_b32_e32 v71, v74
	v_mov_b32_e32 v73, v75
	v_pk_add_f32 v[70:71], v[70:71], v[72:73]
	v_mul_f32_e32 v72, v55, v55
	v_mul_f32_e32 v74, v57, v57
	v_mul_f32_e32 v76, v52, v52
	v_mul_f32_e32 v77, v53, v53
	v_pk_fma_f32 v[72:73], v[54:55], v[54:55], v[72:73] op_sel_hi:[1,1,0]
	v_pk_fma_f32 v[74:75], v[56:57], v[56:57], v[74:75] op_sel_hi:[1,1,0]
	v_mov_b32_e32 v73, v76
	v_mov_b32_e32 v75, v77
	v_pk_add_f32 v[72:73], v[72:73], v[74:75]
	v_pk_mul_f32 v[62:63], v[62:63], v[146:147]
	v_pk_add_f32 v[70:71], v[70:71], v[72:73]
	v_pk_mul_f32 v[72:73], v[126:127], v[86:87]
	v_add_f32_e32 v74, v70, v71
	v_mov_b32_e32 v75, v74
	v_mov_b32_e32 v240, v74
	s_nop 1
	v_permlane16_swap_b32 v75, v240
	v_pk_mul_f32 v[70:71], v[92:93], v[88:89]
	v_cvt_pk_bf16_f32 v68, v72, v73
	v_add_u32_e32 v77, 0x80, v166
	v_cvt_pk_bf16_f32 v69, v70, v71
	s_waitcnt lgkmcnt(0)
	v_add_f32_e32 v74, v75, v240
	v_mov_b32_e32 v75, v74
	v_mov_b32_e32 v240, v74
	s_nop 1
	v_permlane32_swap_b32 v75, v240
	global_store_dwordx4 v[90:91], v[66:69], off offset:64
	v_and_b32_e32 v76, 0x7cf, v77
	v_lshlrev_b32_e32 v70, 6, v76
	s_waitcnt lgkmcnt(0)
	v_add_f32_e32 v66, v75, v240
	v_fmamk_f32 v66, v66, 0x3c800000, v188
	v_rsq_f32_e32 v66, v66
	v_mov_b32_e32 v71, v0
	v_lshl_add_u64 v[70:71], s[62:63], 0, v[70:71]
	v_pk_mul_f32 v[64:65], v[64:65], v[66:67] op_sel_hi:[1,0]
	v_pk_mul_f32 v[62:63], v[62:63], v[66:67] op_sel_hi:[1,0]
	ds_bpermute_b32 v72, v167, v62
	ds_bpermute_b32 v73, v167, v63
	ds_bpermute_b32 v68, v167, v64
	ds_bpermute_b32 v69, v167, v65
	s_and_saveexec_b64 s[10:11], s[4:5]
	s_cbranch_execz .LBB0_360
	global_load_dwordx4 v[220:223], v[250:251], off offset:1024
	global_load_dwordx4 v[224:227], v[250:251], off offset:1040
	global_load_dwordx4 v[228:231], v[250:251], off offset:1056
	global_load_dwordx4 v[232:235], v[250:251], off offset:1072
	s_waitcnt vmcnt(6)
	v_mov_b32_e32 v78, v208
	v_mov_b32_e32 v79, v209
	v_mov_b32_e32 v80, v210
	v_mov_b32_e32 v81, v211
	v_mov_b32_e32 v86, v204
	v_mov_b32_e32 v87, v205
	v_mov_b32_e32 v88, v206
	v_mov_b32_e32 v89, v207
	v_mov_b32_e32 v75, v88
	v_mov_b32_e32 v88, v87
	s_waitcnt lgkmcnt(2)
	v_pk_mul_f32 v[72:73], v[88:89], v[72:73]
	v_mov_b32_e32 v74, v86
	v_cndmask_b32_e64 v73, v73, -v73, s[6:7]
	v_cndmask_b32_e64 v72, v72, -v72, s[6:7]
	v_pk_fma_f32 v[62:63], v[62:63], v[74:75], v[72:73]
	v_mov_b32_e32 v73, v80
	v_mov_b32_e32 v80, v79
	s_waitcnt lgkmcnt(0)
	v_pk_mul_f32 v[68:69], v[80:81], v[68:69]
	v_mov_b32_e32 v72, v78
	v_cndmask_b32_e64 v69, v69, -v69, s[6:7]
	v_cndmask_b32_e64 v68, v68, -v68, s[6:7]
	v_pk_fma_f32 v[64:65], v[64:65], v[72:73], v[68:69]

; __device__ __forceinline__ unsigned cvt_pk_bf16(float lo, float hi) { unsigned r; asm volatile("v_cvt_pk_bf16_f32 %0, %1, %2" : "=v"(r) : "v"(lo), "v"(hi)); return r; }
;     __device__ __forceinline__ static int permpos(int t, int g) { const int dsh = 2 * g; return (t & ((1 << dsh) - 1)) * (2048 >> dsh) + (t >> dsh); }
;     __device__ __forceinline__ void operator()(const f32x4 (&acc)[2][2][4][2], const Unit& u, int wr, int wc, int fr, int fq) const {
;     ...
;                 for (int m = 0; m < 4; ++m) { const int lrow = row0 + ai * HALF + m * 16; const int pos = lrow & 2047, bb = lrow >> 11;
;                     f32x4 y[2][2]; float ss = 0.f;
; #pragma unroll
;                     for (int bj = 0; bj < 2; ++bj)
; #pragma unroll
;                         for (int n = 0; n < 2; ++n) { y[bj][n] = acc[ai][bj][m][n]; ss += (y[bj][n][0] * y[bj][n][0] + y[bj][n][1] * y[bj][n][1]) + (y[bj][n][2] * y[bj][n][2] + y[bj][n][3] * y[bj][n][3]); }
;                     ss += __shfl_xor(ss, 16); ss += __shfl_xor(ss, 32);
;                     const float rs = __builtin_amdgcn_rsqf(ss * (1.0f / 64.0f) + 1e-6f);
; #pragma unroll
;                     for (int bj = 0; bj < 2; ++bj)
; #pragma unroll
;                         for (int n = 0; n < 2; ++n) y[bj][n] = y[bj][n] * gn[bj][n] * rs;
; #pragma unroll
;                     for (int n = 0; n < 2; ++n) { f32x4 pr;
; #pragma unroll
;                         for (int e = 0; e < 4; ++e) pr[e] = __shfl_xor(y[0][n][e], 16);
;                         if (fq < 2) { const f32x4 t0 = *(const f32x4*)(RT + (size_t)pos * 16 + 8 * n), t1 = *(const f32x4*)(RT + (size_t)pos * 16 + 8 * n + 4);
;                             const float co[4] = {t0[0], t0[2], t1[0], t1[2]}, si[4] = {t0[1], t0[3], t1[1], t1[3]};
; #pragma unroll
;                             for (int e = 0; e < 4; ++e) y[0][n][e] = (fq == 0) ? (y[0][n][e] * co[e] - pr[e] * si[e]) : (y[0][n][e] * co[e] + pr[e] * si[e]); } }
;                     bf16_t* rowp = OB + ((size_t)(bb * 24 + gh) * 2048 + permpos(pos, grp)) * 64 + 8 * fq;
; #pragma unroll
;                     for (int bj = 0; bj < 2; ++bj) { const f32x4 v0 = y[bj][0] * sc, v1 = y[bj][1] * sc;
;                         u32x4 w; w.x = cvt_pk_bf16(v0[0], v0[1]); w.y = cvt_pk_bf16(v0[2], v0[3]); w.z = cvt_pk_bf16(v1[0], v1[1]); w.w = cvt_pk_bf16(v1[2], v1[3]);
;                         *(u32x4*)(rowp + 32 * bj) = w; }
.LBB0_362:
	s_or_b64 exec, exec, s[10:11]
	s_waitcnt lgkmcnt(1)
	v_ashrrev_i32_e32 v58, 11, v77
	v_mad_i32_i24 v58, v58, 24, s23
	v_pk_mul_f32 v[54:55], v[54:55], v[138:139]
	v_pk_mul_f32 v[50:51], v[50:51], v[134:135]
	s_waitcnt lgkmcnt(0)
	v_ashrrev_i32_e32 v59, 31, v58
	v_pk_mul_f32 v[54:55], v[54:55], v[66:67]
	v_pk_mul_f32 v[66:67], v[50:51], v[66:67]
	v_and_b32_e32 v50, s22, v76
	v_lshlrev_b64 v[58:59], 18, v[58:59]
	v_mul_u32_u24_e32 v50, s13, v50
	v_lshrrev_b32_e32 v51, s12, v76
	v_lshl_add_u64 v[58:59], v[128:129], 0, v[58:59]
	v_pk_mul_f32 v[56:57], v[56:57], v[140:141]
	v_pk_mul_f32 v[52:53], v[52:53], v[136:137]
	v_add_lshl_u32 v50, v50, v51, 7
	v_mov_b32_e32 v51, v0
	v_mov_b32_e32 v74, v126
	v_mov_b32_e32 v75, v126
	v_pk_mul_f32 v[56:57], v[56:57], v[72:73]
	v_pk_mul_f32 v[70:71], v[52:53], v[72:73]
	v_lshl_add_u64 v[72:73], v[58:59], 0, v[50:51]
	v_pk_mul_f32 v[52:53], v[74:75], v[64:65]
	v_pk_mul_f32 v[50:51], v[126:127], v[62:63]
	v_pk_mul_f32 v[62:63], v[74:75], v[68:69]
	v_pk_mul_f32 v[60:61], v[126:127], v[60:61]
	v_cvt_pk_bf16_f32 v50, v50, v51
	v_cvt_pk_bf16_f32 v51, v52, v53
	s_nop 0
	v_cvt_pk_bf16_f32 v52, v60, v61
	v_cvt_pk_bf16_f32 v53, v62, v63
	global_store_dwordx4 v[72:73], v[50:53], off
	s_nop 1
	v_pk_mul_f32 v[52:53], v[74:75], v[56:57]
	v_pk_mul_f32 v[50:51], v[48:49], v[48:49]
	v_pk_mul_f32 v[56:57], v[46:47], v[46:47]
	v_pk_mul_f32 v[48:49], v[48:49], v[148:149]
	v_pk_mov_b32 v[60:61], v[56:57], v[50:51] op_sel:[1,0]
	v_mov_b32_e32 v57, v51
	v_pk_add_f32 v[50:51], v[60:61], v[56:57]
	v_pk_mul_f32 v[56:57], v[44:45], v[44:45]
	v_pk_mul_f32 v[60:61], v[42:43], v[42:43]
	v_pk_add_f32 v[50:51], v[50:51], v[50:51] op_sel:[0,1] op_sel_hi:[1,0]
	v_pk_mov_b32 v[62:63], v[60:61], v[56:57] op_sel:[1,0]
	v_mov_b32_e32 v61, v57
	v_pk_add_f32 v[56:57], v[62:63], v[60:61]
	v_mul_f32_e32 v60, v34, v34
	v_mul_f32_e32 v61, v35, v35
	v_pk_add_f32 v[56:57], v[56:57], v[56:57] op_sel:[0,1] op_sel_hi:[1,0]
	v_mov_b32_e32 v51, v60
	v_mov_b32_e32 v57, v61
	v_pk_add_f32 v[50:51], v[50:51], v[56:57]
	v_mul_f32_e32 v56, v39, v39
	v_mul_f32_e32 v60, v41, v41
	v_mul_f32_e32 v62, v36, v36
	v_mul_f32_e32 v63, v37, v37
	v_pk_fma_f32 v[56:57], v[38:39], v[38:39], v[56:57] op_sel_hi:[1,1,0]
	v_pk_fma_f32 v[60:61], v[40:41], v[40:41], v[60:61] op_sel_hi:[1,1,0]
	v_mov_b32_e32 v57, v62
	v_mov_b32_e32 v61, v63
	v_pk_add_f32 v[56:57], v[56:57], v[60:61]
	v_pk_mul_f32 v[46:47], v[46:47], v[146:147]
	v_pk_add_f32 v[50:51], v[50:51], v[56:57]
	v_pk_mul_f32 v[56:57], v[126:127], v[66:67]
	v_add_f32_e32 v60, v50, v51
	v_mov_b32_e32 v61, v60
	v_mov_b32_e32 v240, v60
	s_nop 1
	v_permlane16_swap_b32 v61, v240
	v_pk_mul_f32 v[50:51], v[126:127], v[54:55]
	v_pk_mul_f32 v[54:55], v[74:75], v[70:71]
	v_cvt_pk_bf16_f32 v50, v50, v51
	v_cvt_pk_bf16_f32 v51, v52, v53
	s_waitcnt lgkmcnt(0)
	v_add_f32_e32 v60, v61, v240
	v_mov_b32_e32 v61, v60
	v_mov_b32_e32 v240, v60
	s_nop 1
	v_permlane32_swap_b32 v61, v240
	v_cvt_pk_bf16_f32 v52, v56, v57
	v_cvt_pk_bf16_f32 v53, v54, v55
	global_store_dwordx4 v[72:73], v[50:53], off offset:64
	v_or_b32_e32 v62, 16, v76
	s_waitcnt lgkmcnt(0)
	v_add_f32_e32 v50, v61, v240
	v_fmamk_f32 v50, v50, 0x3c800000, v188
	v_rsq_f32_e32 v50, v50
	v_lshlrev_b32_e32 v52, 6, v62
	v_mov_b32_e32 v53, v0
	v_lshl_add_u64 v[52:53], s[62:63], 0, v[52:53]
	v_pk_mul_f32 v[48:49], v[48:49], v[50:51] op_sel_hi:[1,0]
	v_pk_mul_f32 v[46:47], v[46:47], v[50:51] op_sel_hi:[1,0]
	ds_bpermute_b32 v56, v167, v46
	ds_bpermute_b32 v57, v167, v47
	ds_bpermute_b32 v54, v167, v48
	ds_bpermute_b32 v55, v167, v49
	s_and_saveexec_b64 s[10:11], s[4:5]
	s_cbranch_execz .LBB0_364
	global_load_dwordx4 v[204:207], v[250:251], off offset:2048
	global_load_dwordx4 v[208:211], v[250:251], off offset:2064
	global_load_dwordx4 v[212:215], v[250:251], off offset:2080
	global_load_dwordx4 v[216:219], v[250:251], off offset:2096
	s_waitcnt vmcnt(6)
	v_mov_b32_e32 v64, v224
	v_mov_b32_e32 v65, v225
	v_mov_b32_e32 v66, v226
	v_mov_b32_e32 v67, v227
	v_mov_b32_e32 v68, v220
	v_mov_b32_e32 v69, v221
	v_mov_b32_e32 v70, v222
	v_mov_b32_e32 v71, v223
	v_mov_b32_e32 v61, v70
	v_mov_b32_e32 v70, v69
	s_waitcnt lgkmcnt(2)
	v_pk_mul_f32 v[56:57], v[70:71], v[56:57]
	v_mov_b32_e32 v60, v68
	v_cndmask_b32_e64 v57, v57, -v57, s[6:7]
	v_cndmask_b32_e64 v56, v56, -v56, s[6:7]
	v_pk_fma_f32 v[46:47], v[46:47], v[60:61], v[56:57]
	v_mov_b32_e32 v57, v66
	v_mov_b32_e32 v66, v65
	s_waitcnt lgkmcnt(0)
	v_pk_mul_f32 v[54:55], v[66:67], v[54:55]
	v_mov_b32_e32 v56, v64
	v_cndmask_b32_e64 v55, v55, -v55, s[6:7]
	v_cndmask_b32_e64 v54, v54, -v54, s[6:7]
	v_pk_fma_f32 v[48:49], v[48:49], v[56:57], v[54:55]

; __device__ __forceinline__ unsigned cvt_pk_bf16(float lo, float hi) { unsigned r; asm volatile("v_cvt_pk_bf16_f32 %0, %1, %2" : "=v"(r) : "v"(lo), "v"(hi)); return r; }
;     __device__ __forceinline__ static int permpos(int t, int g) { const int dsh = 2 * g; return (t & ((1 << dsh) - 1)) * (2048 >> dsh) + (t >> dsh); }
;     __device__ __forceinline__ void operator()(const f32x4 (&acc)[2][2][4][2], const Unit& u, int wr, int wc, int fr, int fq) const {
;     ...
;                 for (int m = 0; m < 4; ++m) { const int lrow = row0 + ai * HALF + m * 16; const int pos = lrow & 2047, bb = lrow >> 11;
;                     f32x4 y[2][2]; float ss = 0.f;
; #pragma unroll
;                     for (int bj = 0; bj < 2; ++bj)
; #pragma unroll
;                         for (int n = 0; n < 2; ++n) { y[bj][n] = acc[ai][bj][m][n]; ss += (y[bj][n][0] * y[bj][n][0] + y[bj][n][1] * y[bj][n][1]) + (y[bj][n][2] * y[bj][n][2] + y[bj][n][3] * y[bj][n][3]); }
;                     ss += __shfl_xor(ss, 16); ss += __shfl_xor(ss, 32);
;                     const float rs = __builtin_amdgcn_rsqf(ss * (1.0f / 64.0f) + 1e-6f);
; #pragma unroll
;                     for (int bj = 0; bj < 2; ++bj)
; #pragma unroll
;                         for (int n = 0; n < 2; ++n) y[bj][n] = y[bj][n] * gn[bj][n] * rs;
; #pragma unroll
;                     for (int n = 0; n < 2; ++n) { f32x4 pr;
; #pragma unroll
;                         for (int e = 0; e < 4; ++e) pr[e] = __shfl_xor(y[0][n][e], 16);
;                         if (fq < 2) { const f32x4 t0 = *(const f32x4*)(RT + (size_t)pos * 16 + 8 * n), t1 = *(const f32x4*)(RT + (size_t)pos * 16 + 8 * n + 4);
;                             const float co[4] = {t0[0], t0[2], t1[0], t1[2]}, si[4] = {t0[1], t0[3], t1[1], t1[3]};
; #pragma unroll
;                             for (int e = 0; e < 4; ++e) y[0][n][e] = (fq == 0) ? (y[0][n][e] * co[e] - pr[e] * si[e]) : (y[0][n][e] * co[e] + pr[e] * si[e]); } }
;                     bf16_t* rowp = OB + ((size_t)(bb * 24 + gh) * 2048 + permpos(pos, grp)) * 64 + 8 * fq;
; #pragma unroll
;                     for (int bj = 0; bj < 2; ++bj) { const f32x4 v0 = y[bj][0] * sc, v1 = y[bj][1] * sc;
;                         u32x4 w; w.x = cvt_pk_bf16(v0[0], v0[1]); w.y = cvt_pk_bf16(v0[2], v0[3]); w.z = cvt_pk_bf16(v1[0], v1[1]); w.w = cvt_pk_bf16(v1[2], v1[3]);
;                         *(u32x4*)(rowp + 32 * bj) = w; }
.LBB0_366:
	s_or_b64 exec, exec, s[10:11]
	v_pk_mul_f32 v[38:39], v[38:39], v[138:139]
	v_pk_mul_f32 v[34:35], v[34:35], v[134:135]
	v_pk_mul_f32 v[38:39], v[38:39], v[50:51]
	v_pk_mul_f32 v[50:51], v[34:35], v[50:51]
	v_and_b32_e32 v34, s22, v62
	v_mul_u32_u24_e32 v34, s13, v34
	v_lshrrev_b32_e32 v35, s12, v62
	v_pk_mul_f32 v[40:41], v[40:41], v[140:141]
	v_pk_mul_f32 v[36:37], v[36:37], v[136:137]
	v_add_lshl_u32 v34, v34, v35, 7
	v_mov_b32_e32 v35, v0
	s_waitcnt lgkmcnt(1)
	v_mov_b32_e32 v56, v126
	s_waitcnt lgkmcnt(0)
	v_mov_b32_e32 v57, v126
	v_pk_mul_f32 v[40:41], v[40:41], v[54:55]
	v_pk_mul_f32 v[52:53], v[36:37], v[54:55]
	v_lshl_add_u64 v[54:55], v[58:59], 0, v[34:35]
	v_pk_mul_f32 v[36:37], v[56:57], v[48:49]
	v_pk_mul_f32 v[34:35], v[126:127], v[46:47]
	v_pk_mul_f32 v[44:45], v[56:57], v[44:45]
	v_pk_mul_f32 v[42:43], v[126:127], v[42:43]
	v_cvt_pk_bf16_f32 v34, v34, v35
	v_cvt_pk_bf16_f32 v35, v36, v37
	s_nop 0
	v_cvt_pk_bf16_f32 v36, v42, v43
	v_cvt_pk_bf16_f32 v37, v44, v45
	global_store_dwordx4 v[54:55], v[34:37], off
	s_nop 1
	v_pk_mul_f32 v[36:37], v[56:57], v[40:41]
	v_pk_mul_f32 v[34:35], v[32:33], v[32:33]
	v_pk_mul_f32 v[40:41], v[30:31], v[30:31]
	v_pk_mul_f32 v[32:33], v[32:33], v[148:149]
	v_pk_mov_b32 v[42:43], v[40:41], v[34:35] op_sel:[1,0]
	v_mov_b32_e32 v41, v35
	v_pk_add_f32 v[34:35], v[42:43], v[40:41]
	v_pk_mul_f32 v[40:41], v[28:29], v[28:29]
	v_pk_mul_f32 v[42:43], v[26:27], v[26:27]
	v_pk_add_f32 v[34:35], v[34:35], v[34:35] op_sel:[0,1] op_sel_hi:[1,0]
	v_pk_mov_b32 v[44:45], v[42:43], v[40:41] op_sel:[1,0]
	v_mov_b32_e32 v43, v41
	v_pk_add_f32 v[40:41], v[44:45], v[42:43]
	v_mul_f32_e32 v42, v18, v18
	v_mul_f32_e32 v43, v19, v19
	v_pk_add_f32 v[40:41], v[40:41], v[40:41] op_sel:[0,1] op_sel_hi:[1,0]
	v_mov_b32_e32 v35, v42
	v_mov_b32_e32 v41, v43
	v_pk_add_f32 v[34:35], v[34:35], v[40:41]
	v_mul_f32_e32 v40, v23, v23
	v_mul_f32_e32 v42, v25, v25
	v_mul_f32_e32 v44, v20, v20
	v_mul_f32_e32 v45, v21, v21
	v_pk_fma_f32 v[40:41], v[22:23], v[22:23], v[40:41] op_sel_hi:[1,1,0]
	v_pk_fma_f32 v[42:43], v[24:25], v[24:25], v[42:43] op_sel_hi:[1,1,0]
	v_mov_b32_e32 v41, v44
	v_mov_b32_e32 v43, v45
	v_pk_add_f32 v[40:41], v[40:41], v[42:43]
	v_pk_mul_f32 v[30:31], v[30:31], v[146:147]
	v_pk_add_f32 v[34:35], v[34:35], v[40:41]
	v_pk_mul_f32 v[40:41], v[126:127], v[50:51]
	v_add_f32_e32 v42, v34, v35
	v_mov_b32_e32 v43, v42
	v_mov_b32_e32 v240, v42
	s_nop 1
	v_permlane16_swap_b32 v43, v240
	v_pk_mul_f32 v[34:35], v[126:127], v[38:39]
	v_pk_mul_f32 v[38:39], v[56:57], v[52:53]
	v_cvt_pk_bf16_f32 v34, v34, v35
	v_cvt_pk_bf16_f32 v35, v36, v37
	s_waitcnt lgkmcnt(0)
	v_add_f32_e32 v42, v43, v240
	v_mov_b32_e32 v43, v42
	v_mov_b32_e32 v240, v42
	s_nop 1
	v_permlane32_swap_b32 v43, v240
	v_cvt_pk_bf16_f32 v36, v40, v41
	v_cvt_pk_bf16_f32 v37, v38, v39
	global_store_dwordx4 v[54:55], v[34:37], off offset:64
	v_or_b32_e32 v44, 32, v76
	s_waitcnt lgkmcnt(0)
	v_add_f32_e32 v34, v43, v240
	v_fmamk_f32 v34, v34, 0x3c800000, v188
	v_rsq_f32_e32 v34, v34
	v_lshlrev_b32_e32 v36, 6, v44
	v_mov_b32_e32 v37, v0
	v_lshl_add_u64 v[36:37], s[62:63], 0, v[36:37]
	v_pk_mul_f32 v[32:33], v[32:33], v[34:35] op_sel_hi:[1,0]
	v_pk_mul_f32 v[30:31], v[30:31], v[34:35] op_sel_hi:[1,0]
	ds_bpermute_b32 v40, v167, v30
	ds_bpermute_b32 v41, v167, v31
	ds_bpermute_b32 v38, v167, v32
	ds_bpermute_b32 v39, v167, v33
	s_and_saveexec_b64 s[10:11], s[4:5]
	s_cbranch_execz .LBB0_368
	global_load_dwordx4 v[220:223], v[250:251], off offset:3072
	global_load_dwordx4 v[224:227], v[250:251], off offset:3088
	global_load_dwordx4 v[228:231], v[250:251], off offset:3104
	global_load_dwordx4 v[232:235], v[250:251], off offset:3120
	s_waitcnt vmcnt(6)
	v_mov_b32_e32 v46, v208
	v_mov_b32_e32 v47, v209
	v_mov_b32_e32 v48, v210
	v_mov_b32_e32 v49, v211
	v_mov_b32_e32 v50, v204
	v_mov_b32_e32 v51, v205
	v_mov_b32_e32 v52, v206
	v_mov_b32_e32 v53, v207
	v_mov_b32_e32 v43, v52
	v_mov_b32_e32 v52, v51
	s_waitcnt lgkmcnt(2)
	v_pk_mul_f32 v[40:41], v[52:53], v[40:41]
	v_mov_b32_e32 v42, v50
	v_cndmask_b32_e64 v41, v41, -v41, s[6:7]
	v_cndmask_b32_e64 v40, v40, -v40, s[6:7]
	v_pk_fma_f32 v[30:31], v[30:31], v[42:43], v[40:41]
	v_mov_b32_e32 v41, v48
	v_mov_b32_e32 v48, v47
	s_waitcnt lgkmcnt(0)
	v_pk_mul_f32 v[38:39], v[48:49], v[38:39]
	v_mov_b32_e32 v40, v46
	v_cndmask_b32_e64 v39, v39, -v39, s[6:7]
	v_cndmask_b32_e64 v38, v38, -v38, s[6:7]
	v_pk_fma_f32 v[32:33], v[32:33], v[40:41], v[38:39]

; __device__ __forceinline__ unsigned cvt_pk_bf16(float lo, float hi) { unsigned r; asm volatile("v_cvt_pk_bf16_f32 %0, %1, %2" : "=v"(r) : "v"(lo), "v"(hi)); return r; }
;     __device__ __forceinline__ static int permpos(int t, int g) { const int dsh = 2 * g; return (t & ((1 << dsh) - 1)) * (2048 >> dsh) + (t >> dsh); }
;     __device__ __forceinline__ void operator()(const f32x4 (&acc)[2][2][4][2], const Unit& u, int wr, int wc, int fr, int fq) const {
;     ...
;                 for (int m = 0; m < 4; ++m) { const int lrow = row0 + ai * HALF + m * 16; const int pos = lrow & 2047, bb = lrow >> 11;
;                     f32x4 y[2][2]; float ss = 0.f;
; #pragma unroll
;                     for (int bj = 0; bj < 2; ++bj)
; #pragma unroll
;                         for (int n = 0; n < 2; ++n) { y[bj][n] = acc[ai][bj][m][n]; ss += (y[bj][n][0] * y[bj][n][0] + y[bj][n][1] * y[bj][n][1]) + (y[bj][n][2] * y[bj][n][2] + y[bj][n][3] * y[bj][n][3]); }
;                     ss += __shfl_xor(ss, 16); ss += __shfl_xor(ss, 32);
;                     const float rs = __builtin_amdgcn_rsqf(ss * (1.0f / 64.0f) + 1e-6f);
; #pragma unroll
;                     for (int bj = 0; bj < 2; ++bj)
; #pragma unroll
;                         for (int n = 0; n < 2; ++n) y[bj][n] = y[bj][n] * gn[bj][n] * rs;
; #pragma unroll
;                     for (int n = 0; n < 2; ++n) { f32x4 pr;
; #pragma unroll
;                         for (int e = 0; e < 4; ++e) pr[e] = __shfl_xor(y[0][n][e], 16);
;                         if (fq < 2) { const f32x4 t0 = *(const f32x4*)(RT + (size_t)pos * 16 + 8 * n), t1 = *(const f32x4*)(RT + (size_t)pos * 16 + 8 * n + 4);
;                             const float co[4] = {t0[0], t0[2], t1[0], t1[2]}, si[4] = {t0[1], t0[3], t1[1], t1[3]};
; #pragma unroll
;                             for (int e = 0; e < 4; ++e) y[0][n][e] = (fq == 0) ? (y[0][n][e] * co[e] - pr[e] * si[e]) : (y[0][n][e] * co[e] + pr[e] * si[e]); } }
;                     bf16_t* rowp = OB + ((size_t)(bb * 24 + gh) * 2048 + permpos(pos, grp)) * 64 + 8 * fq;
; #pragma unroll
;                     for (int bj = 0; bj < 2; ++bj) { const f32x4 v0 = y[bj][0] * sc, v1 = y[bj][1] * sc;
;                         u32x4 w; w.x = cvt_pk_bf16(v0[0], v0[1]); w.y = cvt_pk_bf16(v0[2], v0[3]); w.z = cvt_pk_bf16(v1[0], v1[1]); w.w = cvt_pk_bf16(v1[2], v1[3]);
;                         *(u32x4*)(rowp + 32 * bj) = w; }
.LBB0_370:
	s_or_b64 exec, exec, s[10:11]
	v_pk_mul_f32 v[22:23], v[22:23], v[138:139]
	v_pk_mul_f32 v[18:19], v[18:19], v[134:135]
	v_pk_mul_f32 v[22:23], v[22:23], v[34:35]
	v_pk_mul_f32 v[34:35], v[18:19], v[34:35]
	v_and_b32_e32 v18, s22, v44
	v_mul_u32_u24_e32 v18, s13, v18
	v_lshrrev_b32_e32 v19, s12, v44
	v_pk_mul_f32 v[24:25], v[24:25], v[140:141]
	v_pk_mul_f32 v[20:21], v[20:21], v[136:137]
	v_add_lshl_u32 v18, v18, v19, 7
	v_mov_b32_e32 v19, v0
	s_waitcnt lgkmcnt(1)
	v_mov_b32_e32 v40, v126
	s_waitcnt lgkmcnt(0)
	v_mov_b32_e32 v41, v126
	v_pk_mul_f32 v[24:25], v[24:25], v[38:39]
	v_pk_mul_f32 v[36:37], v[20:21], v[38:39]
	v_lshl_add_u64 v[38:39], v[58:59], 0, v[18:19]
	v_pk_mul_f32 v[20:21], v[40:41], v[32:33]
	v_pk_mul_f32 v[18:19], v[126:127], v[30:31]
	v_pk_mul_f32 v[28:29], v[40:41], v[28:29]
	v_pk_mul_f32 v[26:27], v[126:127], v[26:27]
	v_cvt_pk_bf16_f32 v18, v18, v19
	v_cvt_pk_bf16_f32 v19, v20, v21
	s_nop 0
	v_cvt_pk_bf16_f32 v20, v26, v27
	v_cvt_pk_bf16_f32 v21, v28, v29
	global_store_dwordx4 v[38:39], v[18:21], off
	s_nop 1
	v_pk_mul_f32 v[20:21], v[40:41], v[24:25]
	v_pk_mul_f32 v[18:19], v[16:17], v[16:17]
	v_pk_mul_f32 v[24:25], v[14:15], v[14:15]
	v_pk_mul_f32 v[16:17], v[16:17], v[148:149]
	v_pk_mov_b32 v[26:27], v[24:25], v[18:19] op_sel:[1,0]
	v_mov_b32_e32 v25, v19
	v_pk_add_f32 v[18:19], v[26:27], v[24:25]
	v_pk_mul_f32 v[24:25], v[12:13], v[12:13]
	v_pk_mul_f32 v[26:27], v[10:11], v[10:11]
	v_pk_add_f32 v[18:19], v[18:19], v[18:19] op_sel:[0,1] op_sel_hi:[1,0]
	v_pk_mov_b32 v[28:29], v[26:27], v[24:25] op_sel:[1,0]
	v_mov_b32_e32 v27, v25
	v_pk_add_f32 v[24:25], v[28:29], v[26:27]
	v_mul_f32_e32 v26, v2, v2
	v_mul_f32_e32 v27, v3, v3
	v_pk_add_f32 v[24:25], v[24:25], v[24:25] op_sel:[0,1] op_sel_hi:[1,0]
	v_mov_b32_e32 v19, v26
	v_mov_b32_e32 v25, v27
	v_pk_add_f32 v[18:19], v[18:19], v[24:25]
	v_mul_f32_e32 v24, v7, v7
	v_mul_f32_e32 v26, v9, v9
	v_mul_f32_e32 v28, v4, v4
	v_mul_f32_e32 v29, v5, v5
	v_pk_fma_f32 v[24:25], v[6:7], v[6:7], v[24:25] op_sel_hi:[1,1,0]
	v_pk_fma_f32 v[26:27], v[8:9], v[8:9], v[26:27] op_sel_hi:[1,1,0]
	v_mov_b32_e32 v25, v28
	v_mov_b32_e32 v27, v29
	v_pk_add_f32 v[24:25], v[24:25], v[26:27]
	v_pk_mul_f32 v[14:15], v[14:15], v[146:147]
	v_pk_add_f32 v[18:19], v[18:19], v[24:25]
	v_pk_mul_f32 v[24:25], v[126:127], v[34:35]
	v_add_f32_e32 v26, v18, v19
	v_mov_b32_e32 v27, v26
	v_mov_b32_e32 v240, v26
	s_nop 1
	v_permlane16_swap_b32 v27, v240
	v_pk_mul_f32 v[18:19], v[126:127], v[22:23]
	v_pk_mul_f32 v[22:23], v[40:41], v[36:37]
	v_cvt_pk_bf16_f32 v18, v18, v19
	v_cvt_pk_bf16_f32 v19, v20, v21
	s_waitcnt lgkmcnt(0)
	v_add_f32_e32 v26, v27, v240
	v_mov_b32_e32 v27, v26
	v_mov_b32_e32 v240, v26
	s_nop 1
	v_permlane32_swap_b32 v27, v240
	v_cvt_pk_bf16_f32 v20, v24, v25
	v_cvt_pk_bf16_f32 v21, v22, v23
	global_store_dwordx4 v[38:39], v[18:21], off offset:64
	v_or_b32_e32 v28, 48, v76
	s_waitcnt lgkmcnt(0)
	v_add_f32_e32 v18, v27, v240
	v_fmamk_f32 v18, v18, 0x3c800000, v188
	v_rsq_f32_e32 v18, v18
	v_lshlrev_b32_e32 v20, 6, v28
	v_mov_b32_e32 v21, v0
	v_lshl_add_u64 v[20:21], s[62:63], 0, v[20:21]
	v_pk_mul_f32 v[16:17], v[16:17], v[18:19] op_sel_hi:[1,0]
	v_pk_mul_f32 v[14:15], v[14:15], v[18:19] op_sel_hi:[1,0]
	ds_bpermute_b32 v24, v167, v14
	ds_bpermute_b32 v25, v167, v15
	ds_bpermute_b32 v22, v167, v16
	ds_bpermute_b32 v23, v167, v17
	s_and_saveexec_b64 s[10:11], s[4:5]
	s_cbranch_execz .LBB0_372
	s_waitcnt vmcnt(2)
	v_mov_b32_e32 v30, v224
	v_mov_b32_e32 v31, v225
	v_mov_b32_e32 v32, v226
	v_mov_b32_e32 v33, v227
	v_mov_b32_e32 v34, v220
	v_mov_b32_e32 v35, v221
	v_mov_b32_e32 v36, v222
	v_mov_b32_e32 v37, v223
	v_mov_b32_e32 v27, v36
	v_mov_b32_e32 v36, v35
	s_waitcnt lgkmcnt(2)
	v_pk_mul_f32 v[24:25], v[36:37], v[24:25]
	v_mov_b32_e32 v26, v34
	v_cndmask_b32_e64 v25, v25, -v25, s[6:7]
	v_cndmask_b32_e64 v24, v24, -v24, s[6:7]
	v_pk_fma_f32 v[14:15], v[14:15], v[26:27], v[24:25]
	v_mov_b32_e32 v25, v32
	v_mov_b32_e32 v32, v31
	s_waitcnt lgkmcnt(0)
	v_pk_mul_f32 v[22:23], v[32:33], v[22:23]
	v_mov_b32_e32 v24, v30
	v_cndmask_b32_e64 v23, v23, -v23, s[6:7]
	v_cndmask_b32_e64 v22, v22, -v22, s[6:7]
	v_pk_fma_f32 v[16:17], v[16:17], v[24:25], v[22:23]
